# stagger variant: half of the teams delayed ~5us at P5 start
# speedup vs baseline: 1.0005x; 1.0005x over previous
;     __host__ __device__ void init(int M_, int G_, int c_) { so.init(M_, 1024, G_, c_); }
;     __host__ __device__ void init(int M_, int G_, int c_) { so.init(M_, 3072, G_, c_); }
;     __host__ __device__ void init(int M_, int start_, int stride_, int limit_) { so.init(M_, 3072, stride_, start_); start = start_; stride = stride_; limit = limit_; }
; __device__ __forceinline__ unsigned long long rt() { return __builtin_amdgcn_s_memrealtime(); }
; __global__ void __launch_bounds__(NWAVES * 64, 2) fwd(Args args) {
;     ...
;     if (IN(5)) {
;         const unsigned long long amp_t0_5 = (PROBE_AMP == 5) ? rt() : 0ull;
;         _Pragma("unroll 1") for (int rep_ = 0; rep_ < ((PROBE == 5) ? 2 : 1); ++rep_) {
;         pg8::Gemm g{OAB, WBAB_T, M, D, 512, D, D, 1}; pg8::MergeOrder S; S.init(M, G, (int)blockIdx.x);
;         pg8::EpiMerge E{GAB, MRG};
;         pg8::gemm_phase<pg8::EpiMerge, pg8::MergeOrder, true, true>(lds + RING_OFF, g, S, E);
.Lstag_loop:
	s_sleep 90
	s_sub_u32 s98, s98, 1
	s_cmp_lg_u32 s98, 0
	s_cbranch_scc1 .Lstag_loop
